# P0 adaLN GEMV: 64 weight loads per thread issued before the staging barrier (k-loop reads registers)
# baseline (speedup 1.0000x reference)
.LBB0_21:
	s_or_b64 exec, exec, s[2:3]
	s_lshl_b32 s2, s64, 5
	s_ashr_i32 s3, s2, 31
	v_ashrrev_i32_e32 v144, 5, v142
	s_lshl_b64 s[4:5], s[2:3], 2
	v_lshlrev_b32_e32 v2, 6, v144
	s_movk_i32 s3, 0x6000
	v_mov_b64_e32 v[0:1], s[4:5]
	v_mad_i64_i32 v[0:1], s[4:5], v2, s3, v[0:1]
	s_load_dwordx16 s[4:19], s[0:1], 0x0
	v_and_b32_e32 v143, 31, v141
	v_lshl_or_b32 v0, v143, 2, v0
	v_mov_b32_e32 v130, 0
	v_lshl_add_u32 v145, v144, 8, 0
	s_waitcnt lgkmcnt(0)
	v_lshl_add_u64 v[128:129], s[10:11], 0, v[0:1]
	s_mov_b32 s13, 0
	s_mov_b32 s12, 0x0
	v_lshl_add_u64 v[244:245], v[128:129], 0, s[12:13]
	global_load_dword v178, v[244:245], off nt
	s_mov_b32 s12, 0x6000
	v_lshl_add_u64 v[244:245], v[128:129], 0, s[12:13]
	global_load_dword v179, v[244:245], off nt
	s_mov_b32 s12, 0xc000
	v_lshl_add_u64 v[244:245], v[128:129], 0, s[12:13]
	global_load_dword v180, v[244:245], off nt
	s_mov_b32 s12, 0x12000
	v_lshl_add_u64 v[244:245], v[128:129], 0, s[12:13]
	global_load_dword v181, v[244:245], off nt
	s_mov_b32 s12, 0x18000
	v_lshl_add_u64 v[244:245], v[128:129], 0, s[12:13]
	global_load_dword v182, v[244:245], off nt
	s_mov_b32 s12, 0x1e000
	v_lshl_add_u64 v[244:245], v[128:129], 0, s[12:13]
	global_load_dword v183, v[244:245], off nt
	s_mov_b32 s12, 0x24000
	v_lshl_add_u64 v[244:245], v[128:129], 0, s[12:13]
	global_load_dword v184, v[244:245], off nt
	s_mov_b32 s12, 0x2a000
	v_lshl_add_u64 v[244:245], v[128:129], 0, s[12:13]
	global_load_dword v185, v[244:245], off nt
	s_mov_b32 s12, 0x30000
	v_lshl_add_u64 v[244:245], v[128:129], 0, s[12:13]
	global_load_dword v186, v[244:245], off nt
	s_mov_b32 s12, 0x36000
	v_lshl_add_u64 v[244:245], v[128:129], 0, s[12:13]
	global_load_dword v187, v[244:245], off nt
	s_mov_b32 s12, 0x3c000
	v_lshl_add_u64 v[244:245], v[128:129], 0, s[12:13]
	global_load_dword v188, v[244:245], off nt
	s_mov_b32 s12, 0x42000
	v_lshl_add_u64 v[244:245], v[128:129], 0, s[12:13]
	global_load_dword v189, v[244:245], off nt
	s_mov_b32 s12, 0x48000
	v_lshl_add_u64 v[244:245], v[128:129], 0, s[12:13]
	global_load_dword v190, v[244:245], off nt
	s_mov_b32 s12, 0x4e000
	v_lshl_add_u64 v[244:245], v[128:129], 0, s[12:13]
	global_load_dword v191, v[244:245], off nt
	s_mov_b32 s12, 0x54000
	v_lshl_add_u64 v[244:245], v[128:129], 0, s[12:13]
	global_load_dword v192, v[244:245], off nt
	s_mov_b32 s12, 0x5a000
	v_lshl_add_u64 v[244:245], v[128:129], 0, s[12:13]
	global_load_dword v193, v[244:245], off nt
	s_mov_b32 s12, 0x60000
	v_lshl_add_u64 v[244:245], v[128:129], 0, s[12:13]
	global_load_dword v194, v[244:245], off nt
	s_mov_b32 s12, 0x66000
	v_lshl_add_u64 v[244:245], v[128:129], 0, s[12:13]
	global_load_dword v195, v[244:245], off nt
	s_mov_b32 s12, 0x6c000
	v_lshl_add_u64 v[244:245], v[128:129], 0, s[12:13]
	global_load_dword v196, v[244:245], off nt
	s_mov_b32 s12, 0x72000
	v_lshl_add_u64 v[244:245], v[128:129], 0, s[12:13]
	global_load_dword v197, v[244:245], off nt
	s_mov_b32 s12, 0x78000
	v_lshl_add_u64 v[244:245], v[128:129], 0, s[12:13]
	global_load_dword v198, v[244:245], off nt
	s_mov_b32 s12, 0x7e000
	v_lshl_add_u64 v[244:245], v[128:129], 0, s[12:13]
	global_load_dword v199, v[244:245], off nt
	s_mov_b32 s12, 0x84000
	v_lshl_add_u64 v[244:245], v[128:129], 0, s[12:13]
	global_load_dword v200, v[244:245], off nt
	s_mov_b32 s12, 0x8a000
	v_lshl_add_u64 v[244:245], v[128:129], 0, s[12:13]
	global_load_dword v201, v[244:245], off nt
	s_mov_b32 s12, 0x90000
	v_lshl_add_u64 v[244:245], v[128:129], 0, s[12:13]
	global_load_dword v202, v[244:245], off nt
	s_mov_b32 s12, 0x96000
	v_lshl_add_u64 v[244:245], v[128:129], 0, s[12:13]
	global_load_dword v203, v[244:245], off nt
	s_mov_b32 s12, 0x9c000
	v_lshl_add_u64 v[244:245], v[128:129], 0, s[12:13]
	global_load_dword v204, v[244:245], off nt
	s_mov_b32 s12, 0xa2000
	v_lshl_add_u64 v[244:245], v[128:129], 0, s[12:13]
	global_load_dword v205, v[244:245], off nt
	s_mov_b32 s12, 0xa8000
	v_lshl_add_u64 v[244:245], v[128:129], 0, s[12:13]
	global_load_dword v206, v[244:245], off nt
	s_mov_b32 s12, 0xae000
	v_lshl_add_u64 v[244:245], v[128:129], 0, s[12:13]
	global_load_dword v207, v[244:245], off nt
	s_mov_b32 s12, 0xb4000
	v_lshl_add_u64 v[244:245], v[128:129], 0, s[12:13]
	global_load_dword v208, v[244:245], off nt
	s_mov_b32 s12, 0xba000
	v_lshl_add_u64 v[244:245], v[128:129], 0, s[12:13]
	global_load_dword v209, v[244:245], off nt
	s_mov_b32 s12, 0xc0000
	v_lshl_add_u64 v[244:245], v[128:129], 0, s[12:13]
	global_load_dword v210, v[244:245], off nt
	s_mov_b32 s12, 0xc6000
	v_lshl_add_u64 v[244:245], v[128:129], 0, s[12:13]
	global_load_dword v211, v[244:245], off nt
	s_mov_b32 s12, 0xcc000
	v_lshl_add_u64 v[244:245], v[128:129], 0, s[12:13]
	global_load_dword v212, v[244:245], off nt
	s_mov_b32 s12, 0xd2000
	v_lshl_add_u64 v[244:245], v[128:129], 0, s[12:13]
	global_load_dword v213, v[244:245], off nt
	s_mov_b32 s12, 0xd8000
	v_lshl_add_u64 v[244:245], v[128:129], 0, s[12:13]
	global_load_dword v214, v[244:245], off nt
	s_mov_b32 s12, 0xde000
	v_lshl_add_u64 v[244:245], v[128:129], 0, s[12:13]
	global_load_dword v215, v[244:245], off nt
	s_mov_b32 s12, 0xe4000
	v_lshl_add_u64 v[244:245], v[128:129], 0, s[12:13]
	global_load_dword v216, v[244:245], off nt
	s_mov_b32 s12, 0xea000
	v_lshl_add_u64 v[244:245], v[128:129], 0, s[12:13]
	global_load_dword v217, v[244:245], off nt
	s_mov_b32 s12, 0xf0000
	v_lshl_add_u64 v[244:245], v[128:129], 0, s[12:13]
	global_load_dword v218, v[244:245], off nt
	s_mov_b32 s12, 0xf6000
	v_lshl_add_u64 v[244:245], v[128:129], 0, s[12:13]
	global_load_dword v219, v[244:245], off nt
	s_mov_b32 s12, 0xfc000
	v_lshl_add_u64 v[244:245], v[128:129], 0, s[12:13]
	global_load_dword v220, v[244:245], off nt
	s_mov_b32 s12, 0x102000
	v_lshl_add_u64 v[244:245], v[128:129], 0, s[12:13]
	global_load_dword v221, v[244:245], off nt
	s_mov_b32 s12, 0x108000
	v_lshl_add_u64 v[244:245], v[128:129], 0, s[12:13]
	global_load_dword v222, v[244:245], off nt
	s_mov_b32 s12, 0x10e000
	v_lshl_add_u64 v[244:245], v[128:129], 0, s[12:13]
	global_load_dword v223, v[244:245], off nt
	s_mov_b32 s12, 0x114000
	v_lshl_add_u64 v[244:245], v[128:129], 0, s[12:13]
	global_load_dword v224, v[244:245], off nt
	s_mov_b32 s12, 0x11a000
	v_lshl_add_u64 v[244:245], v[128:129], 0, s[12:13]
	global_load_dword v225, v[244:245], off nt
	s_mov_b32 s12, 0x120000
	v_lshl_add_u64 v[244:245], v[128:129], 0, s[12:13]
	global_load_dword v226, v[244:245], off nt
	s_mov_b32 s12, 0x126000
	v_lshl_add_u64 v[244:245], v[128:129], 0, s[12:13]
	global_load_dword v227, v[244:245], off nt
	s_mov_b32 s12, 0x12c000
	v_lshl_add_u64 v[244:245], v[128:129], 0, s[12:13]
	global_load_dword v228, v[244:245], off nt
	s_mov_b32 s12, 0x132000
	v_lshl_add_u64 v[244:245], v[128:129], 0, s[12:13]
	global_load_dword v229, v[244:245], off nt
	s_mov_b32 s12, 0x138000
	v_lshl_add_u64 v[244:245], v[128:129], 0, s[12:13]
	global_load_dword v230, v[244:245], off nt
	s_mov_b32 s12, 0x13e000
	v_lshl_add_u64 v[244:245], v[128:129], 0, s[12:13]
	global_load_dword v231, v[244:245], off nt
	s_mov_b32 s12, 0x144000
	v_lshl_add_u64 v[244:245], v[128:129], 0, s[12:13]
	global_load_dword v232, v[244:245], off nt
	s_mov_b32 s12, 0x14a000
	v_lshl_add_u64 v[244:245], v[128:129], 0, s[12:13]
	global_load_dword v233, v[244:245], off nt
	s_mov_b32 s12, 0x150000
	v_lshl_add_u64 v[244:245], v[128:129], 0, s[12:13]
	global_load_dword v234, v[244:245], off nt
	s_mov_b32 s12, 0x156000
	v_lshl_add_u64 v[244:245], v[128:129], 0, s[12:13]
	global_load_dword v235, v[244:245], off nt
	s_mov_b32 s12, 0x15c000
	v_lshl_add_u64 v[244:245], v[128:129], 0, s[12:13]
	global_load_dword v236, v[244:245], off nt
	s_mov_b32 s12, 0x162000
	v_lshl_add_u64 v[244:245], v[128:129], 0, s[12:13]
	global_load_dword v237, v[244:245], off nt
	s_mov_b32 s12, 0x168000
	v_lshl_add_u64 v[244:245], v[128:129], 0, s[12:13]
	global_load_dword v238, v[244:245], off nt
	s_mov_b32 s12, 0x16e000
	v_lshl_add_u64 v[244:245], v[128:129], 0, s[12:13]
	global_load_dword v239, v[244:245], off nt
	s_mov_b32 s12, 0x174000
	v_lshl_add_u64 v[244:245], v[128:129], 0, s[12:13]
	global_load_dword v240, v[244:245], off nt
	s_mov_b32 s12, 0x17a000
	v_lshl_add_u64 v[244:245], v[128:129], 0, s[12:13]
	global_load_dword v241, v[244:245], off nt
	s_mov_b64 s[4:5], 0
	s_mov_b32 s6, 0xc000
	s_mov_b32 s7, 0x12000
	s_mov_b32 s8, 0x18000
	s_mov_b32 s9, 0x1e000
	s_mov_b32 s10, 0x24000
	s_mov_b32 s11, 0x2a000
	s_mov_b32 s12, 0x30000
	s_mov_b32 s13, 0x36000
	s_mov_b32 s14, 0x3c000
	s_mov_b32 s15, 0x42000
	s_mov_b32 s16, 0x48000
	s_mov_b32 s17, 0x4e000
	s_mov_b32 s18, 0x54000
	s_mov_b32 s19, 0x5a000
	v_mov_b32_e32 v131, v130
	v_mov_b32_e32 v132, v130
	v_mov_b32_e32 v133, v130
	v_mov_b32_e32 v134, v130
	v_mov_b32_e32 v135, v130
	v_mov_b32_e32 v136, v130
	v_mov_b32_e32 v137, v130
	s_barrier
.LBB0_22:
	v_lshl_add_u64 v[138:139], v[128:129], 0, s[4:5]
	v_add_co_u32_e32 v146, vcc, s3, v138
	ds_read_b128 v[16:19], v145
	ds_read_b128 v[4:7], v145 offset:16
	ds_read_b128 v[0:3], v145 offset:4096
	ds_read_b128 v[8:11], v145 offset:4112
	ds_read_b128 v[48:51], v145 offset:8192
	ds_read_b128 v[40:43], v145 offset:8208
	ds_read_b128 v[20:23], v145 offset:12288
	ds_read_b128 v[12:15], v145 offset:12304
	ds_read_b128 v[52:55], v145 offset:16384
	ds_read_b128 v[44:47], v145 offset:16400
	ds_read_b128 v[28:31], v145 offset:20480
	ds_read_b128 v[24:27], v145 offset:20496
	ds_read_b128 v[60:63], v145 offset:24576
	ds_read_b128 v[56:59], v145 offset:24592
	ds_read_b128 v[36:39], v145 offset:28672
	ds_read_b128 v[32:35], v145 offset:28688
	v_addc_co_u32_e32 v147, vcc, 0, v139, vcc
	v_add_co_u32_e32 v148, vcc, s6, v138
	ds_read_b128 v[72:75], v145 offset:32
	ds_read_b128 v[68:71], v145 offset:48
	ds_read_b128 v[64:67], v145 offset:4128
	ds_read_b128 v[76:79], v145 offset:4144
	ds_read_b128 v[108:111], v145 offset:8224
	ds_read_b128 v[104:107], v145 offset:8240
	ds_read_b128 v[84:87], v145 offset:12320
	ds_read_b128 v[80:83], v145 offset:12336
	ds_read_b128 v[120:123], v145 offset:16416
	ds_read_b128 v[112:115], v145 offset:16432
	ds_read_b128 v[92:95], v145 offset:20512
	ds_read_b128 v[88:91], v145 offset:20528
	ds_read_b128 v[124:127], v145 offset:24608
	ds_read_b128 v[116:119], v145 offset:24624
	ds_read_b128 v[100:103], v145 offset:28704
	ds_read_b128 v[96:99], v145 offset:28720
	v_addc_co_u32_e32 v149, vcc, 0, v139, vcc
	v_add_co_u32_e32 v150, vcc, s7, v138
	s_waitcnt lgkmcnt(14)
	v_mov_b32_e32 v176, v16
	v_addc_co_u32_e32 v151, vcc, 0, v139, vcc
	v_add_co_u32_e32 v152, vcc, s8, v138
	v_mov_b32_e32 v177, v0
	s_nop 0
	v_addc_co_u32_e32 v153, vcc, 0, v139, vcc
	v_add_co_u32_e32 v154, vcc, s9, v138
	v_mov_b32_e32 v0, v17
	s_nop 0
	v_addc_co_u32_e32 v155, vcc, 0, v139, vcc
	v_add_co_u32_e32 v156, vcc, s10, v138
	v_mov_b32_e32 v16, v18
	s_nop 0
	v_addc_co_u32_e32 v157, vcc, 0, v139, vcc
	v_add_co_u32_e32 v158, vcc, s11, v138
	v_mov_b32_e32 v17, v2
	s_nop 0
	v_addc_co_u32_e32 v159, vcc, 0, v139, vcc
	v_add_co_u32_e32 v160, vcc, s12, v138
	v_mov_b32_e32 v2, v19
	s_nop 0
	v_addc_co_u32_e32 v161, vcc, 0, v139, vcc
	v_add_co_u32_e32 v162, vcc, s13, v138
	v_mov_b32_e32 v18, v48
	s_nop 0
	v_addc_co_u32_e32 v163, vcc, 0, v139, vcc
	v_add_co_u32_e32 v164, vcc, s14, v138
	v_mov_b32_e32 v19, v20
	s_nop 0
	v_addc_co_u32_e32 v165, vcc, 0, v139, vcc
	v_add_co_u32_e32 v166, vcc, s15, v138
	v_mov_b32_e32 v20, v49
	s_nop 0
	v_addc_co_u32_e32 v167, vcc, 0, v139, vcc
	v_add_co_u32_e32 v168, vcc, s16, v138
	v_mov_b32_e32 v48, v50
	s_nop 0
	v_addc_co_u32_e32 v169, vcc, 0, v139, vcc
	v_add_co_u32_e32 v170, vcc, s17, v138
	v_mov_b32_e32 v49, v22
	s_nop 0
	v_addc_co_u32_e32 v171, vcc, 0, v139, vcc
	v_add_co_u32_e32 v172, vcc, s18, v138
	v_mov_b32_e32 v22, v51
	s_nop 0
	v_addc_co_u32_e32 v173, vcc, 0, v139, vcc
	v_add_co_u32_e32 v174, vcc, s19, v138
	v_mov_b32_e32 v50, v52
	s_nop 0
	v_addc_co_u32_e32 v175, vcc, 0, v139, vcc
	v_mov_b32_e32 v146, v179
	s_nop 0
	v_mov_b32_e32 v148, v180
	s_nop 0
	v_mov_b32_e32 v150, v181
	s_nop 0
	v_mov_b32_e32 v152, v182
	s_nop 0
	v_mov_b32_e32 v154, v183
	s_nop 0
	v_mov_b32_e32 v156, v184
	s_nop 0
	v_mov_b32_e32 v158, v185
	s_nop 0
	v_mov_b32_e32 v138, v178
	s_nop 0
	v_mov_b32_e32 v160, v186
	s_nop 0
	v_mov_b32_e32 v162, v187
	s_nop 0
	v_mov_b32_e32 v164, v188
	s_nop 0
	v_mov_b32_e32 v166, v189
	s_nop 0
	v_mov_b32_e32 v168, v190
	s_nop 0
	v_mov_b32_e32 v170, v191
	s_nop 0
	v_mov_b32_e32 v172, v192
	s_nop 0
	v_mov_b32_e32 v174, v193
	v_mov_b32_e32 v51, v28
	v_mov_b32_e32 v28, v53
	v_mov_b32_e32 v52, v54
	v_mov_b32_e32 v53, v30
	v_mov_b32_e32 v30, v55
	v_mov_b32_e32 v54, v60
	v_mov_b32_e32 v55, v36
	v_mov_b32_e32 v36, v61
	v_mov_b32_e32 v60, v62
	v_mov_b32_e32 v61, v38
	v_mov_b32_e32 v38, v63
	v_mov_b32_e32 v62, v4
	v_mov_b32_e32 v63, v8
	v_mov_b32_e32 v8, v5
	v_mov_b32_e32 v4, v6
	v_mov_b32_e32 v5, v10
	v_mov_b32_e32 v10, v7
	v_mov_b32_e32 v6, v40
	v_mov_b32_e32 v7, v12
	v_mov_b32_e32 v12, v41
	v_mov_b32_e32 v40, v42
	v_mov_b32_e32 v41, v14
	v_mov_b32_e32 v14, v43
	v_mov_b32_e32 v42, v44
	v_mov_b32_e32 v43, v24
	v_mov_b32_e32 v24, v45
	v_mov_b32_e32 v44, v46
	v_mov_b32_e32 v45, v26
	v_mov_b32_e32 v26, v47
	v_mov_b32_e32 v46, v56
	v_mov_b32_e32 v47, v32
	v_mov_b32_e32 v32, v57
	v_mov_b32_e32 v56, v58
	v_mov_b32_e32 v57, v34
	v_mov_b32_e32 v34, v59
	v_mov_b32_e32 v58, v72
	s_waitcnt lgkmcnt(13)
	v_mov_b32_e32 v59, v64
	v_mov_b32_e32 v64, v73
	v_mov_b32_e32 v72, v74
	v_mov_b32_e32 v73, v66
	v_mov_b32_e32 v66, v75
	s_waitcnt lgkmcnt(11)
	v_mov_b32_e32 v74, v108
	s_waitcnt lgkmcnt(9)
	v_mov_b32_e32 v75, v84
	v_mov_b32_e32 v84, v109
	v_mov_b32_e32 v108, v110
	v_mov_b32_e32 v109, v86
	v_mov_b32_e32 v86, v111
	s_waitcnt lgkmcnt(7)
	v_mov_b32_e32 v110, v120
	s_waitcnt lgkmcnt(5)
	v_mov_b32_e32 v111, v92
	v_mov_b32_e32 v92, v121
	v_mov_b32_e32 v120, v122
	v_mov_b32_e32 v121, v94
	v_mov_b32_e32 v94, v123
	s_waitcnt lgkmcnt(3)
	v_mov_b32_e32 v122, v124
	s_waitcnt lgkmcnt(1)
	v_mov_b32_e32 v123, v100
	v_mov_b32_e32 v100, v125
	v_mov_b32_e32 v124, v126
	v_mov_b32_e32 v125, v102
	v_mov_b32_e32 v102, v127
	v_mov_b32_e32 v126, v68
	v_mov_b32_e32 v127, v76
	v_mov_b32_e32 v76, v69
	v_mov_b32_e32 v68, v70
	v_mov_b32_e32 v69, v78
	v_mov_b32_e32 v78, v71
	v_mov_b32_e32 v70, v104
	v_mov_b32_e32 v71, v80
	v_mov_b32_e32 v80, v105
	v_mov_b32_e32 v104, v106
	v_mov_b32_e32 v105, v82
	v_mov_b32_e32 v82, v107
	v_mov_b32_e32 v106, v112
	v_mov_b32_e32 v107, v88
	v_mov_b32_e32 v88, v113
	v_mov_b32_e32 v112, v114
	v_mov_b32_e32 v113, v90
	v_mov_b32_e32 v90, v115
	v_mov_b32_e32 v114, v116
	s_waitcnt lgkmcnt(0)
	v_mov_b32_e32 v115, v96
	v_mov_b32_e32 v96, v117
	v_mov_b32_e32 v116, v118
	v_mov_b32_e32 v117, v98
	v_mov_b32_e32 v98, v119
	s_waitcnt vmcnt(0)
	v_pk_fma_f32 v[118:119], v[138:139], v[176:177], v[130:131] op_sel_hi:[0,1,1]
	v_pk_fma_f32 v[18:19], v[138:139], v[18:19], v[132:133] op_sel_hi:[0,1,1]
	v_pk_fma_f32 v[50:51], v[138:139], v[50:51], v[134:135] op_sel_hi:[0,1,1]
	v_pk_fma_f32 v[54:55], v[138:139], v[54:55], v[136:137] op_sel_hi:[0,1,1]
	v_pk_fma_f32 v[0:1], v[146:147], v[0:1], v[118:119] op_sel_hi:[0,1,1]
	v_pk_fma_f32 v[18:19], v[146:147], v[20:21], v[18:19] op_sel_hi:[0,1,1]
	v_pk_fma_f32 v[20:21], v[146:147], v[28:29], v[50:51] op_sel_hi:[0,1,1]
	v_pk_fma_f32 v[28:29], v[146:147], v[36:37], v[54:55] op_sel_hi:[0,1,1]
	v_pk_fma_f32 v[0:1], v[148:149], v[16:17], v[0:1] op_sel_hi:[0,1,1]
	v_pk_fma_f32 v[16:17], v[148:149], v[48:49], v[18:19] op_sel_hi:[0,1,1]
	v_pk_fma_f32 v[18:19], v[148:149], v[52:53], v[20:21] op_sel_hi:[0,1,1]
	v_pk_fma_f32 v[20:21], v[148:149], v[60:61], v[28:29] op_sel_hi:[0,1,1]
	v_pk_fma_f32 v[0:1], v[150:151], v[2:3], v[0:1] op_sel_hi:[0,1,1]
	v_pk_fma_f32 v[2:3], v[150:151], v[22:23], v[16:17] op_sel_hi:[0,1,1]
	v_pk_fma_f32 v[16:17], v[150:151], v[30:31], v[18:19] op_sel_hi:[0,1,1]
	v_pk_fma_f32 v[18:19], v[150:151], v[38:39], v[20:21] op_sel_hi:[0,1,1]
	v_pk_fma_f32 v[0:1], v[152:153], v[62:63], v[0:1] op_sel_hi:[0,1,1]
	v_pk_fma_f32 v[2:3], v[152:153], v[6:7], v[2:3] op_sel_hi:[0,1,1]
	v_pk_fma_f32 v[6:7], v[152:153], v[42:43], v[16:17] op_sel_hi:[0,1,1]
	v_pk_fma_f32 v[16:17], v[152:153], v[46:47], v[18:19] op_sel_hi:[0,1,1]
	v_pk_fma_f32 v[0:1], v[154:155], v[8:9], v[0:1] op_sel_hi:[0,1,1]
	v_pk_fma_f32 v[2:3], v[154:155], v[12:13], v[2:3] op_sel_hi:[0,1,1]
	v_pk_fma_f32 v[6:7], v[154:155], v[24:25], v[6:7] op_sel_hi:[0,1,1]
	v_pk_fma_f32 v[8:9], v[154:155], v[32:33], v[16:17] op_sel_hi:[0,1,1]
	v_pk_fma_f32 v[0:1], v[156:157], v[4:5], v[0:1] op_sel_hi:[0,1,1]
	v_pk_fma_f32 v[2:3], v[156:157], v[40:41], v[2:3] op_sel_hi:[0,1,1]
	v_pk_fma_f32 v[4:5], v[156:157], v[44:45], v[6:7] op_sel_hi:[0,1,1]
	v_pk_fma_f32 v[6:7], v[156:157], v[56:57], v[8:9] op_sel_hi:[0,1,1]
	v_pk_fma_f32 v[0:1], v[158:159], v[10:11], v[0:1] op_sel_hi:[0,1,1]
	v_pk_fma_f32 v[2:3], v[158:159], v[14:15], v[2:3] op_sel_hi:[0,1,1]
	v_pk_fma_f32 v[4:5], v[158:159], v[26:27], v[4:5] op_sel_hi:[0,1,1]
	v_pk_fma_f32 v[6:7], v[158:159], v[34:35], v[6:7] op_sel_hi:[0,1,1]
	s_waitcnt vmcnt(7)
	v_pk_fma_f32 v[0:1], v[160:161], v[58:59], v[0:1] op_sel_hi:[0,1,1]
	v_pk_fma_f32 v[2:3], v[160:161], v[74:75], v[2:3] op_sel_hi:[0,1,1]
	v_pk_fma_f32 v[4:5], v[160:161], v[110:111], v[4:5] op_sel_hi:[0,1,1]
	v_pk_fma_f32 v[6:7], v[160:161], v[122:123], v[6:7] op_sel_hi:[0,1,1]
	s_waitcnt vmcnt(6)
	v_pk_fma_f32 v[0:1], v[162:163], v[64:65], v[0:1] op_sel_hi:[0,1,1]
	v_pk_fma_f32 v[2:3], v[162:163], v[84:85], v[2:3] op_sel_hi:[0,1,1]
	v_pk_fma_f32 v[4:5], v[162:163], v[92:93], v[4:5] op_sel_hi:[0,1,1]
	v_pk_fma_f32 v[6:7], v[162:163], v[100:101], v[6:7] op_sel_hi:[0,1,1]
	s_waitcnt vmcnt(5)
	v_pk_fma_f32 v[0:1], v[164:165], v[72:73], v[0:1] op_sel_hi:[0,1,1]
	v_pk_fma_f32 v[2:3], v[164:165], v[108:109], v[2:3] op_sel_hi:[0,1,1]
	v_pk_fma_f32 v[4:5], v[164:165], v[120:121], v[4:5] op_sel_hi:[0,1,1]
	v_pk_fma_f32 v[6:7], v[164:165], v[124:125], v[6:7] op_sel_hi:[0,1,1]
	s_waitcnt vmcnt(4)
	v_pk_fma_f32 v[0:1], v[166:167], v[66:67], v[0:1] op_sel_hi:[0,1,1]
	v_pk_fma_f32 v[2:3], v[166:167], v[86:87], v[2:3] op_sel_hi:[0,1,1]
	v_pk_fma_f32 v[4:5], v[166:167], v[94:95], v[4:5] op_sel_hi:[0,1,1]
	v_pk_fma_f32 v[6:7], v[166:167], v[102:103], v[6:7] op_sel_hi:[0,1,1]
	s_waitcnt vmcnt(3)
	v_pk_fma_f32 v[0:1], v[168:169], v[126:127], v[0:1] op_sel_hi:[0,1,1]
	v_pk_fma_f32 v[2:3], v[168:169], v[70:71], v[2:3] op_sel_hi:[0,1,1]
	v_pk_fma_f32 v[4:5], v[168:169], v[106:107], v[4:5] op_sel_hi:[0,1,1]
	v_pk_fma_f32 v[6:7], v[168:169], v[114:115], v[6:7] op_sel_hi:[0,1,1]
	s_add_u32 s4, s4, 0x60000
	s_waitcnt vmcnt(2)
	v_pk_fma_f32 v[0:1], v[170:171], v[76:77], v[0:1] op_sel_hi:[0,1,1]
	v_pk_fma_f32 v[2:3], v[170:171], v[80:81], v[2:3] op_sel_hi:[0,1,1]
	v_pk_fma_f32 v[4:5], v[170:171], v[88:89], v[4:5] op_sel_hi:[0,1,1]
	v_pk_fma_f32 v[6:7], v[170:171], v[96:97], v[6:7] op_sel_hi:[0,1,1]
	s_addc_u32 s5, s5, 0
	s_waitcnt vmcnt(1)
	v_pk_fma_f32 v[0:1], v[172:173], v[68:69], v[0:1] op_sel_hi:[0,1,1]
	v_pk_fma_f32 v[2:3], v[172:173], v[104:105], v[2:3] op_sel_hi:[0,1,1]
	v_pk_fma_f32 v[4:5], v[172:173], v[112:113], v[4:5] op_sel_hi:[0,1,1]
	v_pk_fma_f32 v[6:7], v[172:173], v[116:117], v[6:7] op_sel_hi:[0,1,1]
	v_add_u32_e32 v145, 64, v145
	s_cmp_eq_u32 s4, 0x180000
	s_waitcnt vmcnt(0)
	v_pk_fma_f32 v[130:131], v[174:175], v[78:79], v[0:1] op_sel_hi:[0,1,1]
	v_pk_fma_f32 v[132:133], v[174:175], v[82:83], v[2:3] op_sel_hi:[0,1,1]
	v_pk_fma_f32 v[134:135], v[174:175], v[90:91], v[4:5] op_sel_hi:[0,1,1]
	v_pk_fma_f32 v[136:137], v[174:175], v[98:99], v[6:7] op_sel_hi:[0,1,1]
	v_mov_b32_e32 v178, v194
	v_mov_b32_e32 v179, v195
	v_mov_b32_e32 v180, v196
	v_mov_b32_e32 v181, v197
	v_mov_b32_e32 v182, v198
	v_mov_b32_e32 v183, v199
	v_mov_b32_e32 v184, v200
	v_mov_b32_e32 v185, v201
	v_mov_b32_e32 v186, v202
	v_mov_b32_e32 v187, v203
	v_mov_b32_e32 v188, v204
	v_mov_b32_e32 v189, v205
	v_mov_b32_e32 v190, v206
	v_mov_b32_e32 v191, v207
	v_mov_b32_e32 v192, v208
	v_mov_b32_e32 v193, v209
	v_mov_b32_e32 v194, v210
	v_mov_b32_e32 v195, v211
	v_mov_b32_e32 v196, v212
	v_mov_b32_e32 v197, v213
	v_mov_b32_e32 v198, v214
	v_mov_b32_e32 v199, v215
	v_mov_b32_e32 v200, v216
	v_mov_b32_e32 v201, v217
	v_mov_b32_e32 v202, v218
	v_mov_b32_e32 v203, v219
	v_mov_b32_e32 v204, v220
	v_mov_b32_e32 v205, v221
	v_mov_b32_e32 v206, v222
	v_mov_b32_e32 v207, v223
	v_mov_b32_e32 v208, v224
	v_mov_b32_e32 v209, v225
	v_mov_b32_e32 v210, v226
	v_mov_b32_e32 v211, v227
	v_mov_b32_e32 v212, v228
	v_mov_b32_e32 v213, v229
	v_mov_b32_e32 v214, v230
	v_mov_b32_e32 v215, v231
	v_mov_b32_e32 v216, v232
	v_mov_b32_e32 v217, v233
	v_mov_b32_e32 v218, v234
	v_mov_b32_e32 v219, v235
	v_mov_b32_e32 v220, v236
	v_mov_b32_e32 v221, v237
	v_mov_b32_e32 v222, v238
	v_mov_b32_e32 v223, v239
	v_mov_b32_e32 v224, v240
	v_mov_b32_e32 v225, v241
	s_cbranch_scc0 .LBB0_22
	v_lshlrev_b32_e32 v1, 10, v144
	v_lshlrev_b32_e32 v0, 2, v143
	v_add3_u32 v1, 0, v1, v0
	s_movk_i32 s3, 0x100
	v_add_u32_e32 v1, 0x8000, v1
	v_cmp_gt_i32_e32 vcc, s3, v142
	ds_write2_b32 v1, v130, v131 offset1:32
	ds_write2_b32 v1, v132, v133 offset0:64 offset1:96
	ds_write2_b32 v1, v134, v135 offset0:128 offset1:160
	ds_write2_b32 v1, v136, v137 offset0:192 offset1:224
	s_waitcnt lgkmcnt(0)
	s_barrier
	s_and_saveexec_b64 s[4:5], vcc
	s_cbranch_execz .LBB0_25
	s_load_dwordx16 s[8:23], s[0:1], 0x0
	v_or_b32_e32 v4, s2, v143
	v_ashrrev_i32_e32 v5, 31, v4
	v_and_b32_e32 v1, 0x3fffffe0, v142
	s_movk_i32 s3, 0x1800
	s_waitcnt lgkmcnt(0)
	v_mov_b32_e32 v2, s16
	v_mov_b32_e32 v3, s17
	v_lshl_add_u64 v[2:3], v[4:5], 2, v[2:3]
	global_load_dword v18, v[2:3], off
	v_lshlrev_b32_e32 v1, 2, v1
	v_mul_lo_u32 v2, v144, s3
	v_add3_u32 v14, 0, v1, v0
	v_add_u32_e32 v16, s2, v2
	ds_read2st64_b32 v[0:1], v14 offset0:128 offset1:132
	ds_read2st64_b32 v[2:3], v14 offset0:136 offset1:140
	ds_read2st64_b32 v[4:5], v14 offset0:144 offset1:148
	ds_read2st64_b32 v[6:7], v14 offset0:152 offset1:156
	ds_read2st64_b32 v[8:9], v14 offset0:160 offset1:164
	ds_read2st64_b32 v[10:11], v14 offset0:168 offset1:172
	ds_read2st64_b32 v[12:13], v14 offset0:176 offset1:180
	ds_read2st64_b32 v[14:15], v14 offset0:184 offset1:188
	v_or_b32_e32 v16, v16, v143
	v_ashrrev_i32_e32 v17, 31, v16
	s_waitcnt vmcnt(0) lgkmcnt(7)
	v_add_f32_e32 v0, v18, v0
	v_add_f32_e32 v0, v0, v1
	s_waitcnt lgkmcnt(6)
	v_add_f32_e32 v0, v0, v2
	v_add_f32_e32 v0, v0, v3
	s_waitcnt lgkmcnt(5)
	v_add_f32_e32 v0, v0, v4
	v_add_f32_e32 v0, v0, v5
	s_waitcnt lgkmcnt(4)
	v_add_f32_e32 v0, v0, v6
	v_add_f32_e32 v0, v0, v7
	s_waitcnt lgkmcnt(3)
	v_add_f32_e32 v0, v0, v8
	v_add_f32_e32 v0, v0, v9
	s_waitcnt lgkmcnt(2)
	v_add_f32_e32 v0, v0, v10
	v_add_f32_e32 v0, v0, v11
	s_waitcnt lgkmcnt(1)
	v_add_f32_e32 v0, v0, v12
	v_add_f32_e32 v0, v0, v13
	s_waitcnt lgkmcnt(0)
	v_add_f32_e32 v0, v0, v14
	v_add_f32_e32 v2, v0, v15
	v_lshl_add_u64 v[0:1], v[16:17], 2, s[82:83]
	global_store_dword v[0:1], v2, off
